# tile-walk regrouping (WGM=4) also for REC_IN and ATT_IN; REC rotation dropped
# baseline (speedup 1.0000x reference)
; DI int obid() { int b = blockIdx.x; asm volatile("" : "+s"(b)); return b; }
; #define STAGE(bufoff, GB) do { const char* g_ = (GB); \
;         _Pragma("unroll") for (int i_ = 0; i_ < 2; ++i_) __builtin_amdgcn_global_load_lds((const unsigned*)(g_ + voff[i_]), (LAS3 unsigned*)(L + (bufoff) + stoff + i_ * 8192), 16, 0, 0); } while (0)
; #define VOFF_INIT() do { _Pragma("unroll") for (int i = 0; i < 2; ++i) { int R, C; stage_rc((wid * 64 + olane()) * 16 + i * 8192, R, C); voff[i] = (unsigned)(R * K + C) * 2u; } } while (0)
; template <int EPI>
; DI void gemm_phase(const bf16_t* __restrict__ A, const bf16_t* __restrict__ Bt, const int K, const int N, const Params& p, const int layer_j, char* lds) {
;     ...
;     if (obid() >= nwg) return;
;     int pm, pn;
;     TILE_COORDS(obid(), pm, pn);
;     const size_t kstep = 128, hstep = (size_t)HALF * K * 2, tstep = 2 * hstep;
;     const char* cA = (const char*)A + (size_t)pm * tstep; const char* cB = (const char*)Bt + (size_t)pn * tstep;
;     f32x4 acc[2][2][4][2];
; #pragma unroll
;     for (int a = 0; a < 2; ++a)
; #pragma unroll
;         for (int b = 0; b < 2; ++b)
; #pragma unroll
;             for (int m = 0; m < 4; ++m)
; #pragma unroll
;                 for (int n = 0; n < 2; ++n) acc[a][b][m][n] = (f32x4){0.f, 0.f, 0.f, 0.f};
;     bf16x8 At[4][2], B0[2][2], B1[2][2];
;     {
;         unsigned voff[2]; VOFF_INIT();
;         asm volatile("s_waitcnt vmcnt(0) lgkmcnt(0)" ::: "memory");
;         __syncthreads();
;         STAGE(SB(0, 0), cB); STAGE(SB(0, 1), cB + hstep); STAGE(SA(0, 0), cA); STAGE(SA(0, 1), cA + hstep);
.LBB0_326:
	s_ashr_i32 s4, s6, 3
	s_lshl_b64 s[18:19], s[14:15], 23
	s_add_u32 s5, s68, s18
	s_addc_u32 s6, s69, s19
	s_add_u32 s36, s5, 0x1081000
	s_addc_u32 s37, s6, 0
	s_add_i32 s4, s7, s4
	s_ashr_i32 s5, s4, 31
	s_lshr_b32 s5, s5, 28
	s_add_i32 s5, s4, s5
	s_ashr_i32 s6, s5, 4
	s_sub_i32 s7, 64, s6
	s_min_i32 s7, s7, 1
	s_abs_i32 s8, s7
	v_cvt_f32_u32_e32 v0, s8
	s_sub_i32 s10, 0, s8
	s_and_b32 s5, s5, -16
	s_sub_i32 s5, s4, s5
	v_rcp_iflag_f32_e32 v0, v0
	s_abs_i32 s4, s5
	s_xor_b32 s9, s5, s7
	s_ashr_i32 s9, s9, 31
	v_mul_f32_e32 v0, 0x4f7ffffe, v0
	v_cvt_u32_f32_e32 v0, v0
	v_add_u32_e32 v187, 0x10000, v184
	v_add_u32_e32 v188, 0x12000, v184
	v_add_u32_e32 v189, 0x14000, v184
	v_readfirstlane_b32 s11, v0
	s_mul_i32 s10, s10, s11
	s_mul_hi_u32 s10, s11, s10
	s_add_i32 s11, s11, s10
	s_mul_hi_u32 s10, s4, s11
	s_mul_i32 s11, s10, s8
	s_sub_i32 s4, s4, s11
	s_add_i32 s12, s10, 1
	s_sub_i32 s11, s4, s8
	s_cmp_ge_u32 s4, s8
	s_cselect_b32 s10, s12, s10
	s_cselect_b32 s4, s11, s4
	s_add_i32 s11, s10, 1
	s_cmp_ge_u32 s4, s8
	s_cselect_b32 s4, s11, s10
	s_xor_b32 s4, s4, s9
	v_mbcnt_lo_u32_b32 v0, -1, 0
	v_mbcnt_hi_u32_b32 v0, -1, v0
	s_sub_i32 s4, s4, s9
	v_add_u32_e32 v1, s71, v0
	v_lshlrev_b32_e32 v2, 4, v1
	v_ashrrev_i32_e32 v1, 6, v1
	s_mul_i32 s7, s4, s7
	v_lshrrev_b32_e32 v4, 31, v1
	s_sub_i32 s5, s5, s7
	v_add_u32_e32 v4, v1, v4
	s_add_i32 s8, s6, s5
	s_and_b32 s5, s8, 3
	s_mul_i32 s5, s5, 16
	s_add_i32 s5, s5, s4
	s_and_b32 s8, s8, -4
	s_and_b32 s7, s5, 3
	s_add_i32 s8, s8, s7
	s_lshr_b32 s4, s5, 2
	s_ashr_i32 s5, s4, 31
	v_and_b32_e32 v3, 32, v0
	v_and_b32_e32 v5, 0x3fffffe, v4
	s_lshl_b64 s[30:31], s[4:5], 19
	v_sub_u32_e32 v1, v1, v5
	v_bitop3_b32 v2, v2, v3, 48 bitop3:0x6c
	v_lshlrev_b32_e32 v3, 14, v4
	v_lshlrev_b32_e32 v0, 9, v0
	s_movk_i32 s5, 0x7800
	v_lshlrev_b32_e32 v1, 6, v1
	v_and_b32_e32 v3, 0xffff8000, v3
	v_and_or_b32 v0, v0, s5, v2
	v_add3_u32 v32, v1, v3, v0
	v_mbcnt_lo_u32_b32 v0, -1, 0
	v_mbcnt_hi_u32_b32 v0, -1, v0
	s_ashr_i32 s9, s8, 31
	v_add_lshl_u32 v1, v0, s71, 4
	v_add_u32_e32 v2, 0x2000, v1
	v_ashrrev_i32_e32 v2, 10, v2
	s_lshl_b64 s[28:29], s[8:9], 19
	v_and_b32_e32 v3, 32, v0
	v_lshrrev_b32_e32 v4, 31, v2
	s_add_u32 s10, s82, s28
	v_add_u32_e32 v4, v2, v4
	v_bitop3_b32 v1, v1, v3, 48 bitop3:0x6c
	v_lshlrev_b32_e32 v0, 9, v0
	s_addc_u32 s11, s83, s29
	v_lshlrev_b32_e32 v3, 14, v4
	v_and_or_b32 v0, v0, s5, v1
	s_movk_i32 s5, 0x8000
	v_and_b32_e32 v5, 0x3fffffe, v4
	v_and_or_b32 v0, v3, s5, v0
	s_add_u32 s12, s36, s30
	v_readfirstlane_b32 s5, v187
	v_sub_u32_e32 v2, v2, v5
	s_addc_u32 s13, s37, s31
	s_mov_b32 m0, s5
	v_readfirstlane_b32 s5, v188
	v_lshl_add_u32 v0, v2, 6, v0
	s_waitcnt vmcnt(0) lgkmcnt(0)
	s_waitcnt lgkmcnt(0)
	s_barrier
	global_load_lds_dwordx4 v32, s[12:13]
	s_mov_b32 m0, s5
	s_add_u32 s6, s12, 0x40000
	v_readfirstlane_b32 s5, v189
	v_add_u32_e32 v190, 0x16000, v184
	global_load_lds_dwordx4 v0, s[12:13]
	s_addc_u32 s7, s13, 0
	s_mov_b32 m0, s5
	v_readfirstlane_b32 s5, v190
	global_load_lds_dwordx4 v32, s[6:7]
	s_mov_b32 m0, s5
	v_readfirstlane_b32 s5, v184
	v_add_u32_e32 v191, 0x2000, v184
	global_load_lds_dwordx4 v0, s[6:7]
	s_mov_b32 m0, s5
	v_readfirstlane_b32 s5, v191
	v_add_u32_e32 v204, 0x4000, v184
	global_load_lds_dwordx4 v32, s[10:11]
	s_mov_b32 m0, s5
	s_add_u32 s6, s10, 0x40000
	v_readfirstlane_b32 s5, v204
	v_add_u32_e32 v205, 0x6000, v184
	global_load_lds_dwordx4 v0, s[10:11]
	s_addc_u32 s7, s11, 0
	s_mov_b32 m0, s5
	v_readfirstlane_b32 s5, v205
	global_load_lds_dwordx4 v32, s[6:7]
	s_mov_b32 m0, s5
	s_nop 0
	global_load_lds_dwordx4 v0, s[6:7]
	v_readlane_b32 s6, v254, 10
	v_readlane_b32 s7, v254, 11
	s_andn2_b64 vcc, exec, s[6:7]
	s_nop 0
	v_cndmask_b32_e64 v1, 0, 1, s[6:7]
	v_cmp_ne_u32_e64 s[16:17], 1, v1
	s_nop 1
	v_writelane_b32 v255, s16, 6
	s_nop 1
	v_writelane_b32 v255, s17, 7
	s_cbranch_vccnz .LBB0_328
	s_barrier

; DI int obid() { int b = blockIdx.x; asm volatile("" : "+s"(b)); return b; }
; DI int ogrid() { int g = gridDim.x; asm volatile("" : "+s"(g)); return g; }
; template <int EPI>
; DI void gemm_phase(const bf16_t* __restrict__ A, const bf16_t* __restrict__ Bt, const int K, const int N, const Params& p, const int layer_j, char* lds) {
;     ...
;         const int Lnext = (ui + 1) * ogrid() + obid();
;         const bool has_next = Lnext < nwg;
;         int pm2 = pm, pn2 = pn;
;         if (has_next) TILE_COORDS(Lnext, pm2, pn2);
.LBB0_336:
	s_ashr_i32 s5, s5, 3
	s_add_i32 s5, s22, s5
	s_ashr_i32 s9, s5, 31
	s_lshr_b32 s9, s9, 28
	s_add_i32 s9, s5, s9
	s_ashr_i32 s20, s9, 4
	s_and_b32 s9, s9, -16
	s_sub_i32 s22, s5, s9
	s_and_b32 s5, s20, 3
	s_mul_i32 s5, s5, 16
	s_add_i32 s5, s5, s22
	s_and_b32 s20, s20, -4
	s_and_b32 s9, s5, 3
	s_add_i32 s20, s20, s9
	s_lshr_b32 s22, s5, 2

; DI int obid() { int b = blockIdx.x; asm volatile("" : "+s"(b)); return b; }
; #define STAGE(bufoff, GB) do { const char* g_ = (GB); \
;         _Pragma("unroll") for (int i_ = 0; i_ < 2; ++i_) __builtin_amdgcn_global_load_lds((const unsigned*)(g_ + voff[i_]), (LAS3 unsigned*)(L + (bufoff) + stoff + i_ * 8192), 16, 0, 0); } while (0)
; #define VOFF_INIT() do { _Pragma("unroll") for (int i = 0; i < 2; ++i) { int R, C; stage_rc((wid * 64 + olane()) * 16 + i * 8192, R, C); voff[i] = (unsigned)(R * K + C) * 2u; } } while (0)
; template <int EPI>
; DI void gemm_phase(const bf16_t* __restrict__ A, const bf16_t* __restrict__ Bt, const int K, const int N, const Params& p, const int layer_j, char* lds) {
;     ...
;     if (obid() >= nwg) return;
;     int pm, pn;
;     TILE_COORDS(obid(), pm, pn);
;     const size_t kstep = 128, hstep = (size_t)HALF * K * 2, tstep = 2 * hstep;
;     const char* cA = (const char*)A + (size_t)pm * tstep; const char* cB = (const char*)Bt + (size_t)pn * tstep;
;     f32x4 acc[2][2][4][2];
; #pragma unroll
;     for (int a = 0; a < 2; ++a)
; #pragma unroll
;         for (int b = 0; b < 2; ++b)
; #pragma unroll
;             for (int m = 0; m < 4; ++m)
; #pragma unroll
;                 for (int n = 0; n < 2; ++n) acc[a][b][m][n] = (f32x4){0.f, 0.f, 0.f, 0.f};
;     bf16x8 At[4][2], B0[2][2], B1[2][2];
;     {
;         unsigned voff[2]; VOFF_INIT();
;         asm volatile("s_waitcnt vmcnt(0) lgkmcnt(0)" ::: "memory");
;         __syncthreads();
;         STAGE(SB(0, 0), cB); STAGE(SB(0, 1), cB + hstep); STAGE(SA(0, 0), cA); STAGE(SA(0, 1), cA + hstep);
.LBB0_364:
	s_andn2_b64 vcc, exec, s[4:5]
	s_cbranch_vccnz .LBB0_391
	s_waitcnt vmcnt(0)
	v_mbcnt_lo_u32_b32 v0, -1, 0
	v_mbcnt_hi_u32_b32 v0, -1, v0
	v_readlane_b32 s4, v254, 7
	v_and_b32_e32 v1, 15, v0
	v_and_b32_e32 v4, 48, v0
	v_or_b32_e32 v2, s4, v1
	v_lshlrev_b32_e32 v3, 6, v2
	s_movk_i32 s4, 0x3c0
	v_lshlrev_b32_e32 v5, 4, v0
	v_and_or_b32 v3, v3, s4, v4
	v_and_b32_e32 v5, 0xfffffc00, v5
	v_readlane_b32 s4, v254, 8
	v_lshlrev_b32_e32 v2, 2, v2
	v_add_lshl_u32 v138, v0, s71, 4
	v_add_u32_e32 v6, s4, v5
	v_and_b32_e32 v2, 32, v2
	v_readlane_b32 s4, v254, 9
	v_lshlrev_b32_e32 v0, 2, v0
	v_bitop3_b32 v139, v3, v6, v2 bitop3:0xde
	v_lshl_or_b32 v1, v1, 6, v4
	v_add_u32_e32 v2, s4, v5
	v_and_b32_e32 v0, 32, v0
	v_bitop3_b32 v140, v1, v2, v0 bitop3:0xde
	s_mov_b32 s4, s2
	s_cmpk_gt_i32 s4, 0x2ff
	s_cbranch_scc1 .LBB0_391
	v_readlane_b32 s4, v255, 10
	s_mul_i32 s13, s4, 0x600000
	v_readlane_b32 s5, v255, 11
	s_mul_hi_u32 s12, s4, 0x600000
	s_add_u32 s4, s68, s13
	s_addc_u32 s5, s69, s12
	s_add_u32 s34, s4, 0x81000
	s_mov_b32 s4, s2
	s_addc_u32 s35, s5, 0
	s_ashr_i32 s5, s4, 31
	s_lshr_b32 s5, s5, 29
	s_add_i32 s5, s4, s5
	s_ashr_i32 s6, s5, 3
	s_and_b32 s5, s5, -8
	s_sub_i32 s4, s4, s5
	s_cmp_lt_i32 s4, 0
	s_movk_i32 s5, 0x61
	s_cselect_b32 s5, s5, 0x60
	s_mul_i32 s4, s5, s4
	s_add_i32 s4, s4, s6
	s_mul_hi_i32 s5, s4, 0x2aaaaaab
	s_lshr_b32 s6, s5, 31
	s_ashr_i32 s5, s5, 1
	s_add_i32 s5, s5, s6
	s_sub_i32 s6, 64, s5
	s_min_i32 s6, s6, 1
	s_abs_i32 s7, s6
	v_cvt_f32_u32_e32 v0, s7
	s_sub_i32 s10, 0, s7
	s_mul_i32 s8, s5, 12
	s_sub_i32 s4, s4, s8
	v_rcp_iflag_f32_e32 v0, v0
	s_abs_i32 s9, s4
	s_xor_b32 s8, s4, s6
	s_ashr_i32 s8, s8, 31
	v_mul_f32_e32 v0, 0x4f7ffffe, v0
	v_cvt_u32_f32_e32 v0, v0
	v_add_u32_e32 v141, 0x10000, v138
	v_add_u32_e32 v142, 0x12000, v138
	v_add_u32_e32 v143, 0x14000, v138
	v_readfirstlane_b32 s11, v0
	s_mul_i32 s10, s10, s11
	s_mul_hi_u32 s10, s11, s10
	s_add_i32 s11, s11, s10
	s_mul_hi_u32 s10, s9, s11
	s_mul_i32 s11, s10, s7
	s_sub_i32 s9, s9, s11
	s_add_i32 s11, s10, 1
	s_sub_i32 s14, s9, s7
	s_cmp_ge_u32 s9, s7
	s_cselect_b32 s10, s11, s10
	s_cselect_b32 s9, s14, s9
	s_add_i32 s11, s10, 1
	s_cmp_ge_u32 s9, s7
	s_cselect_b32 s7, s11, s10
	v_mbcnt_lo_u32_b32 v0, -1, 0
	v_mbcnt_hi_u32_b32 v0, -1, v0
	s_xor_b32 s7, s7, s8
	v_add_u32_e32 v1, s71, v0
	v_lshlrev_b32_e32 v2, 4, v1
	v_ashrrev_i32_e32 v1, 6, v1
	s_sub_i32 s24, s7, s8
	v_lshrrev_b32_e32 v4, 31, v1
	s_mul_i32 s6, s24, s6
	v_add_u32_e32 v4, v1, v4
	s_sub_i32 s4, s4, s6
	v_and_b32_e32 v3, 32, v0
	v_and_b32_e32 v5, 0x3fffffe, v4
	s_add_i32 s22, s5, s4
	s_and_b32 s5, s22, 3
	s_mul_i32 s5, s5, 12
	s_add_i32 s5, s5, s24
	s_and_b32 s22, s22, -4
	s_and_b32 s6, s5, 3
	s_add_i32 s22, s22, s6
	s_lshr_b32 s24, s5, 2
	v_sub_u32_e32 v1, v1, v5
	v_bitop3_b32 v2, v2, v3, 48 bitop3:0x6c
	v_lshlrev_b32_e32 v3, 14, v4
	v_lshlrev_b32_e32 v0, 9, v0
	s_movk_i32 s4, 0x7800
	v_lshlrev_b32_e32 v1, 6, v1
	v_and_b32_e32 v3, 0xffff8000, v3
	v_and_or_b32 v0, v0, s4, v2
	v_add3_u32 v32, v1, v3, v0
	v_mbcnt_lo_u32_b32 v0, -1, 0
	v_mbcnt_hi_u32_b32 v0, -1, v0
	s_ashr_i32 s23, s22, 31
	v_add_lshl_u32 v1, v0, s71, 4
	v_add_u32_e32 v2, 0x2000, v1
	s_ashr_i32 s25, s24, 31
	v_ashrrev_i32_e32 v2, 10, v2
	s_lshl_b64 s[26:27], s[22:23], 19
	s_lshl_b64 s[28:29], s[24:25], 19
	v_and_b32_e32 v3, 32, v0
	v_lshrrev_b32_e32 v4, 31, v2
	s_add_u32 s6, s82, s26
	v_add_u32_e32 v4, v2, v4
	v_bitop3_b32 v1, v1, v3, 48 bitop3:0x6c
	v_lshlrev_b32_e32 v0, 9, v0
	s_addc_u32 s7, s83, s27
	v_lshlrev_b32_e32 v3, 14, v4
	v_and_or_b32 v0, v0, s4, v1
	s_movk_i32 s4, 0x8000
	v_and_b32_e32 v5, 0x3fffffe, v4
	v_and_or_b32 v0, v3, s4, v0
	s_add_u32 s8, s34, s28
	v_readfirstlane_b32 s4, v141
	v_sub_u32_e32 v2, v2, v5
	s_addc_u32 s9, s35, s29
	s_mov_b32 m0, s4
	v_readfirstlane_b32 s4, v142
	v_lshl_add_u32 v0, v2, 6, v0
	s_waitcnt vmcnt(0) lgkmcnt(0)
	s_waitcnt lgkmcnt(0)
	s_barrier
	global_load_lds_dwordx4 v32, s[8:9]
	s_mov_b32 m0, s4
	s_add_u32 s4, s8, 0x40000
	v_readfirstlane_b32 s10, v143
	v_add_u32_e32 v144, 0x16000, v138
	global_load_lds_dwordx4 v0, s[8:9]
	s_addc_u32 s5, s9, 0
	s_mov_b32 m0, s10
	v_readfirstlane_b32 s10, v144
	global_load_lds_dwordx4 v32, s[4:5]
	s_mov_b32 m0, s10
	v_add_u32_e32 v145, 0x2000, v138
	global_load_lds_dwordx4 v0, s[4:5]
	v_readfirstlane_b32 s4, v138
	s_mov_b32 m0, s4
	v_readfirstlane_b32 s4, v145
	v_add_u32_e32 v146, 0x4000, v138
	global_load_lds_dwordx4 v32, s[6:7]
	s_mov_b32 m0, s4
	s_add_u32 s4, s6, 0x40000
	v_readfirstlane_b32 s10, v146
	v_add_u32_e32 v147, 0x6000, v138
	global_load_lds_dwordx4 v0, s[6:7]
	s_addc_u32 s5, s7, 0
	s_mov_b32 m0, s10
	v_readfirstlane_b32 s10, v147
	global_load_lds_dwordx4 v32, s[4:5]
	s_mov_b32 m0, s10
	v_readlane_b32 s10, v254, 10
	global_load_lds_dwordx4 v0, s[4:5]
	v_readlane_b32 s11, v254, 11
	s_andn2_b64 vcc, exec, s[10:11]
	s_nop 0
	v_cndmask_b32_e64 v1, 0, 1, s[10:11]
	v_cmp_ne_u32_e64 s[4:5], 1, v1
	s_cbranch_vccnz .LBB0_368
	s_barrier

; DI int obid() { int b = blockIdx.x; asm volatile("" : "+s"(b)); return b; }
; DI int ogrid() { int g = gridDim.x; asm volatile("" : "+s"(g)); return g; }
; template <int EPI>
; DI void gemm_phase(const bf16_t* __restrict__ A, const bf16_t* __restrict__ Bt, const int K, const int N, const Params& p, const int layer_j, char* lds) {
;     ...
;         const int Lnext = (ui + 1) * ogrid() + obid();
;         const bool has_next = Lnext < nwg;
;         int pm2 = pm, pn2 = pn;
;         if (has_next) TILE_COORDS(Lnext, pm2, pn2);
.LBB0_371:
	s_mov_b32 s12, s70
	s_add_i32 s39, s39, 1
	s_mul_i32 s13, s12, s39
	s_mov_b32 s12, s2
	s_add_i32 s13, s13, s12
	s_cmpk_lt_i32 s13, 0x300
	s_cselect_b64 s[16:17], -1, 0
	s_cmpk_gt_i32 s13, 0x2ff
	s_mov_b32 s14, s24
	s_mov_b32 s12, s22
	s_cbranch_scc1 .LBB0_373
	s_ashr_i32 s12, s13, 31
	s_lshr_b32 s12, s12, 29
	s_add_i32 s12, s13, s12
	s_ashr_i32 s14, s12, 3
	s_and_b32 s12, s12, -8
	s_sub_i32 s12, s13, s12
	s_cmp_lt_i32 s12, 0
	s_movk_i32 s13, 0x61
	s_cselect_b32 s13, s13, 0x60
	s_mul_i32 s12, s13, s12
	s_add_i32 s13, s12, s14
	s_mul_hi_i32 s12, s13, 0x2aaaaaab
	s_lshr_b32 s14, s12, 31
	s_ashr_i32 s12, s12, 1
	s_add_i32 s12, s12, s14
	s_mul_i32 s14, s12, 12
	s_sub_i32 s14, s13, s14
	s_and_b32 s13, s12, 3
	s_mul_i32 s13, s13, 12
	s_add_i32 s13, s13, s14
	s_and_b32 s12, s12, -4
	s_and_b32 s15, s13, 3
	s_add_i32 s12, s12, s15
	s_lshr_b32 s14, s13, 2
